# S5: fma-chain scan, burst LDS reads, no per-chunk store-completion stall
# speedup vs baseline: 1.0174x; 1.0112x over previous
.LBB0_98:
	s_or_b64 exec, exec, s[2:3]
	v_or_b32_e32 v0, v2, v204
	v_lshlrev_b64 v[8:9], 12, v[0:1]
	s_mov_b64 s[2:3], 0x1000
	v_lshlrev_b64 v[6:7], 8, v[0:1]
	v_lshl_add_u64 v[8:9], v[8:9], 0, s[2:3]
	v_cndmask_b32_e64 v7, v9, v7, s[44:45]
	v_cndmask_b32_e64 v6, v8, v6, s[44:45]
	v_readlane_b32 s4, v252, 48
	v_lshlrev_b32_e32 v4, 4, v4
	v_lshlrev_b64 v[6:7], 12, v[6:7]
	v_readlane_b32 s18, v252, 62
	v_readlane_b32 s19, v252, 63
	v_ashrrev_i32_e32 v5, 31, v4
	v_add_u32_e32 v0, -16, v3
	v_lshl_add_u64 v[6:7], s[18:19], 0, v[6:7]
	v_lshlrev_b64 v[12:13], 2, v[4:5]
	v_cndmask_b32_e64 v0, v0, 0, s[40:41]
	v_lshl_add_u64 v[4:5], v[6:7], 0, v[12:13]
	v_mov_b32_e32 v149, v1
	v_or_b32_e32 v0, v0, v205
	v_lshl_add_u64 v[156:157], v[4:5], 0, v[148:149]
	v_lshlrev_b64 v[4:5], 12, v[0:1]
	v_subrev_u32_e32 v0, 32, v3
	v_cndmask_b32_e64 v0, v0, 16, s[40:41]
	v_or_b32_e32 v0, v0, v205
	s_waitcnt vmcnt(12)
	v_lshlrev_b64 v[14:15], 12, v[0:1]
	v_lshl_add_u64 v[8:9], v[156:157], 0, v[4:5]
	v_lshl_add_u64 v[14:15], v[156:157], 0, v[14:15]
	global_load_dwordx4 v[4:7], v[8:9], off offset:16
	s_nop 0
	global_load_dwordx4 v[8:11], v[8:9], off
	s_nop 0
	global_load_dwordx4 v[98:101], v[14:15], off offset:16
	global_load_dwordx4 v[102:105], v[14:15], off
	v_lshrrev_b32_e32 v149, 4, v3
	v_subrev_u32_e32 v210, 48, v3
	v_mov_b32_e32 v3, v1
	v_lshlrev_b64 v[14:15], 12, v[2:3]
	v_lshl_add_u64 v[162:163], v[146:147], 0, v[12:13]
	v_lshlrev_b64 v[12:13], 8, v[2:3]
	v_or_b32_e32 v0, 0x1000, v14
	v_cndmask_b32_e64 v164, v0, v12, s[44:45]
	v_or_b32_e32 v0, 1, v2
	v_cndmask_b32_e64 v165, v15, v13, s[44:45]
	v_lshlrev_b64 v[12:13], 12, v[0:1]
	v_lshlrev_b64 v[2:3], 8, v[0:1]
	v_lshl_add_u64 v[12:13], v[12:13], 0, s[2:3]
	v_cndmask_b32_e64 v167, v13, v3, s[44:45]
	v_cndmask_b32_e64 v166, v12, v2, s[44:45]
	v_mov_b32_e32 v2, v1
	v_mov_b32_e32 v3, v1
	v_mov_b32_e32 v0, v1
	v_mov_b64_e32 v[108:109], v[2:3]
	v_mov_b64_e32 v[112:113], v[2:3]
	s_waitcnt vmcnt(5)
	v_pk_mov_b32 v[158:159], v[152:153], v[152:153] op_sel:[1,0]
	s_waitcnt vmcnt(4)
	v_pk_mov_b32 v[160:161], v[154:155], v[154:155] op_sel:[1,0]
	s_mov_b32 s28, 0
	s_mov_b32 s34, 32
	v_mov_b32_e32 v168, v152
	v_mov_b32_e32 v169, v152
	v_mov_b32_e32 v170, v153
	v_mov_b32_e32 v171, v153
	v_mov_b32_e32 v172, v154
	v_mov_b32_e32 v173, v154
	v_mov_b32_e32 v174, v155
	v_mov_b32_e32 v175, v155
	s_mov_b64 s[2:3], 0
	v_mov_b64_e32 v[106:107], v[0:1]
	v_mov_b64_e32 v[110:111], v[0:1]
	v_readlane_b32 s5, v252, 49
	v_readlane_b32 s6, v252, 50
	v_readlane_b32 s7, v252, 51
	v_readlane_b32 s8, v252, 52
	v_readlane_b32 s9, v252, 53
	v_readlane_b32 s10, v252, 54
	v_readlane_b32 s11, v252, 55
	v_readlane_b32 s12, v252, 56
	v_readlane_b32 s13, v252, 57
	v_readlane_b32 s14, v252, 58
	v_readlane_b32 s15, v252, 59
	v_readlane_b32 s16, v252, 60
	v_readlane_b32 s17, v252, 61
	s_waitcnt vmcnt(2)
	s_branch .LBB0_100

.LBB0_102:
	s_or_b64 exec, exec, s[20:21]
	v_cvt_pk_bf16_f32 v18, v8, v9
	v_cvt_pk_bf16_f32 v19, v10, v11
	v_cvt_pk_bf16_f32 v20, v4, v5
	v_cvt_pk_bf16_f32 v21, v6, v7
	v_pk_mul_f32 v[178:179], v[158:159], v[178:179] op_sel_hi:[1,0]
	v_pk_mul_f32 v[176:177], v[160:161], v[176:177] op_sel_hi:[1,0]
	v_mfma_f32_32x32x16_bf16 v[34:49], v[18:21], v[66:69], 0
	v_fma_f32 v184, v152, v182, -v178
	v_fma_f32 v185, v153, v183, -v179
	v_fma_f32 v178, v152, v182, v178
	v_fma_f32 v179, v153, v182, v179
	v_fma_f32 v182, v154, v180, -v176
	v_fma_f32 v183, v155, v181, -v177
	v_pk_fma_f32 v[176:177], v[154:155], v[180:181], v[176:177] op_sel_hi:[1,0,1]
	v_mov_b32_e32 v185, v179
	v_mov_b32_e32 v183, v177
	v_add_u32_e32 v212, 0xe00, v207
	v_mfma_f32_32x32x16_bf16 v[2:17], v[18:21], v[70:73], 0
	v_add_u32_e32 v180, 0xc00, v207
	v_add_u32_e32 v213, 0xa00, v207
	v_add_u32_e32 v211, 0x800, v207
	v_add_u32_e32 v0, 0x400, v207
	v_mfma_f32_32x32x16_bf16 v[50:65], v[18:21], v[74:77], 0
	v_mfma_f32_32x32x16_bf16 v[18:33], v[18:21], v[78:81], 0
	s_and_saveexec_b64 s[20:21], s[42:43]
	s_xor_b64 s[20:21], exec, s[20:21]
	s_cbranch_execz .LBB0_104
	s_nop 7
	v_add_f32_e32 v49, v184, v49
	v_add_f32_e32 v17, v182, v17
	v_add_f32_e32 v65, v185, v65
	v_add_f32_e32 v33, v183, v33
	v_cvt_pk_bf16_f32 v184, v49, v65
	v_cvt_pk_bf16_f32 v185, v17, v33
	ds_write_b32 v207, v184 offset:4080
	ds_write_b32 v207, v185 offset:4208
	v_fmac_f32_e32 v48, v152, v49
	v_fmac_f32_e32 v64, v152, v65
	v_fmac_f32_e32 v16, v154, v17
	v_fmac_f32_e32 v32, v154, v33
	v_fma_f32 v48, -v153, v65, v48
	v_fmac_f32_e32 v64, v153, v49
	v_fma_f32 v16, -v155, v33, v16
	v_fmac_f32_e32 v32, v155, v17
	v_cvt_pk_bf16_f32 v184, v48, v64
	v_cvt_pk_bf16_f32 v185, v16, v32
	ds_write_b32 v207, v184 offset:3808
	ds_write_b32 v207, v185 offset:3936
	v_fmac_f32_e32 v47, v152, v48
	v_fmac_f32_e32 v63, v152, v64
	v_fmac_f32_e32 v15, v154, v16
	v_fmac_f32_e32 v31, v154, v32
	v_fma_f32 v47, -v153, v64, v47
	v_fmac_f32_e32 v63, v153, v48
	v_fma_f32 v15, -v155, v32, v15
	v_fmac_f32_e32 v31, v155, v16
	v_cvt_pk_bf16_f32 v184, v47, v63
	v_cvt_pk_bf16_f32 v185, v15, v31
	ds_write_b32 v207, v184 offset:3536
	ds_write_b32 v207, v185 offset:3664
	v_fmac_f32_e32 v46, v152, v47
	v_fmac_f32_e32 v62, v152, v63
	v_fmac_f32_e32 v14, v154, v15
	v_fmac_f32_e32 v30, v154, v31
	v_fma_f32 v46, -v153, v63, v46
	v_fmac_f32_e32 v62, v153, v47
	v_fma_f32 v14, -v155, v31, v14
	v_fmac_f32_e32 v30, v155, v15
	v_cvt_pk_bf16_f32 v184, v46, v62
	v_cvt_pk_bf16_f32 v185, v14, v30
	ds_write_b32 v207, v184 offset:3264
	ds_write_b32 v207, v185 offset:3392
	v_fmac_f32_e32 v45, v152, v46
	v_fmac_f32_e32 v61, v152, v62
	v_fmac_f32_e32 v13, v154, v14
	v_fmac_f32_e32 v29, v154, v30
	v_fma_f32 v45, -v153, v62, v45
	v_fmac_f32_e32 v61, v153, v46
	v_fma_f32 v13, -v155, v30, v13
	v_fmac_f32_e32 v29, v155, v14
	v_cvt_pk_bf16_f32 v184, v45, v61
	v_cvt_pk_bf16_f32 v185, v13, v29
	ds_write_b32 v207, v184 offset:2992
	ds_write_b32 v207, v185 offset:3120
	v_fmac_f32_e32 v44, v152, v45
	v_fmac_f32_e32 v60, v152, v61
	v_fmac_f32_e32 v12, v154, v13
	v_fmac_f32_e32 v28, v154, v29
	v_fma_f32 v44, -v153, v61, v44
	v_fmac_f32_e32 v60, v153, v45
	v_fma_f32 v12, -v155, v29, v12
	v_fmac_f32_e32 v28, v155, v13
	v_cvt_pk_bf16_f32 v184, v44, v60
	v_cvt_pk_bf16_f32 v185, v12, v28
	ds_write_b32 v207, v184 offset:2720
	ds_write_b32 v207, v185 offset:2848
	v_fmac_f32_e32 v43, v152, v44
	v_fmac_f32_e32 v59, v152, v60
	v_fmac_f32_e32 v11, v154, v12
	v_fmac_f32_e32 v27, v154, v28
	v_fma_f32 v43, -v153, v60, v43
	v_fmac_f32_e32 v59, v153, v44
	v_fma_f32 v11, -v155, v28, v11
	v_fmac_f32_e32 v27, v155, v12
	v_cvt_pk_bf16_f32 v184, v43, v59
	v_cvt_pk_bf16_f32 v185, v11, v27
	ds_write_b32 v207, v184 offset:2448
	ds_write_b32 v207, v185 offset:2576
	v_fmac_f32_e32 v42, v152, v43
	v_fmac_f32_e32 v58, v152, v59
	v_fmac_f32_e32 v10, v154, v11
	v_fmac_f32_e32 v26, v154, v27
	v_fma_f32 v42, -v153, v59, v42
	v_fmac_f32_e32 v58, v153, v43
	v_fma_f32 v10, -v155, v27, v10
	v_fmac_f32_e32 v26, v155, v11
	v_cvt_pk_bf16_f32 v184, v42, v58
	v_cvt_pk_bf16_f32 v185, v10, v26
	ds_write_b32 v207, v184 offset:2176
	ds_write_b32 v207, v185 offset:2304
	v_fmac_f32_e32 v41, v152, v42
	v_fmac_f32_e32 v57, v152, v58
	v_fmac_f32_e32 v9, v154, v10
	v_fmac_f32_e32 v25, v154, v26
	v_fma_f32 v41, -v153, v58, v41
	v_fmac_f32_e32 v57, v153, v42
	v_fma_f32 v9, -v155, v26, v9
	v_fmac_f32_e32 v25, v155, v10
	v_cvt_pk_bf16_f32 v184, v41, v57
	v_cvt_pk_bf16_f32 v185, v9, v25
	ds_write_b32 v207, v184 offset:1904
	ds_write_b32 v207, v185 offset:2032
	v_fmac_f32_e32 v40, v152, v41
	v_fmac_f32_e32 v56, v152, v57
	v_fmac_f32_e32 v8, v154, v9
	v_fmac_f32_e32 v24, v154, v25
	v_fma_f32 v40, -v153, v57, v40
	v_fmac_f32_e32 v56, v153, v41
	v_fma_f32 v8, -v155, v25, v8
	v_fmac_f32_e32 v24, v155, v9
	v_cvt_pk_bf16_f32 v184, v40, v56
	v_cvt_pk_bf16_f32 v185, v8, v24
	ds_write_b32 v207, v184 offset:1632
	ds_write_b32 v207, v185 offset:1760
	v_fmac_f32_e32 v39, v152, v40
	v_fmac_f32_e32 v55, v152, v56
	v_fmac_f32_e32 v7, v154, v8
	v_fmac_f32_e32 v23, v154, v24
	v_fma_f32 v39, -v153, v56, v39
	v_fmac_f32_e32 v55, v153, v40
	v_fma_f32 v7, -v155, v24, v7
	v_fmac_f32_e32 v23, v155, v8
	v_cvt_pk_bf16_f32 v184, v39, v55
	v_cvt_pk_bf16_f32 v185, v7, v23
	ds_write_b32 v207, v184 offset:1360
	ds_write_b32 v207, v185 offset:1488
	v_fmac_f32_e32 v38, v152, v39
	v_fmac_f32_e32 v54, v152, v55
	v_fmac_f32_e32 v6, v154, v7
	v_fmac_f32_e32 v22, v154, v23
	v_fma_f32 v38, -v153, v55, v38
	v_fmac_f32_e32 v54, v153, v39
	v_fma_f32 v6, -v155, v23, v6
	v_fmac_f32_e32 v22, v155, v7
	v_cvt_pk_bf16_f32 v184, v38, v54
	v_cvt_pk_bf16_f32 v185, v6, v22
	ds_write_b32 v207, v184 offset:1088
	ds_write_b32 v207, v185 offset:1216
	v_fmac_f32_e32 v37, v152, v38
	v_fmac_f32_e32 v53, v152, v54
	v_fmac_f32_e32 v5, v154, v6
	v_fmac_f32_e32 v21, v154, v22
	v_fma_f32 v37, -v153, v54, v37
	v_fmac_f32_e32 v53, v153, v38
	v_fma_f32 v5, -v155, v22, v5
	v_fmac_f32_e32 v21, v155, v6
	v_cvt_pk_bf16_f32 v184, v37, v53
	v_cvt_pk_bf16_f32 v185, v5, v21
	ds_write_b32 v207, v184 offset:816
	ds_write_b32 v207, v185 offset:944
	v_fmac_f32_e32 v36, v152, v37
	v_fmac_f32_e32 v52, v152, v53
	v_fmac_f32_e32 v4, v154, v5
	v_fmac_f32_e32 v20, v154, v21
	v_fma_f32 v36, -v153, v53, v36
	v_fmac_f32_e32 v52, v153, v37
	v_fma_f32 v4, -v155, v21, v4
	v_fmac_f32_e32 v20, v155, v5
	v_cvt_pk_bf16_f32 v184, v36, v52
	v_cvt_pk_bf16_f32 v185, v4, v20
	ds_write_b32 v207, v184 offset:544
	ds_write_b32 v207, v185 offset:672
	v_fmac_f32_e32 v35, v152, v36
	v_fmac_f32_e32 v51, v152, v52
	v_fmac_f32_e32 v3, v154, v4
	v_fmac_f32_e32 v19, v154, v20
	v_fma_f32 v35, -v153, v52, v35
	v_fmac_f32_e32 v51, v153, v36
	v_fma_f32 v3, -v155, v20, v3
	v_fmac_f32_e32 v19, v155, v4
	v_cvt_pk_bf16_f32 v184, v35, v51
	v_cvt_pk_bf16_f32 v185, v3, v19
	ds_write_b32 v207, v184 offset:272
	ds_write_b32 v207, v185 offset:400
	v_fmac_f32_e32 v34, v152, v35
	v_fmac_f32_e32 v50, v152, v51
	v_fmac_f32_e32 v2, v154, v3
	v_fmac_f32_e32 v18, v154, v19
	v_fma_f32 v34, -v153, v51, v34
	v_fmac_f32_e32 v50, v153, v35
	v_fma_f32 v2, -v155, v19, v2
	v_fmac_f32_e32 v18, v155, v3
	v_cvt_pk_bf16_f32 v184, v34, v50
	v_cvt_pk_bf16_f32 v185, v2, v18
	ds_write_b32 v207, v184 offset:0
	ds_write_b32 v207, v185 offset:128
	v_mov_b32_e32 v179, v34
	v_mov_b32_e32 v178, v50
	v_mov_b32_e32 v177, v2
	v_mov_b32_e32 v176, v18
